# Peeled first K-loop iteration: first-touch MFMAs use SrcC=0, accumulator zeroing block removed (all three GEMM instances)
# speedup vs baseline: 1.1005x; 1.0005x over previous
.LBB0_389:
	s_ashr_i32 s29, s28, 31
	s_lshl_b64 s[4:5], s[28:29], 19
	s_add_u32 s30, s12, s4
	s_addc_u32 s31, s13, s5
	s_and_b64 s[4:5], s[40:41], exec
	s_cselect_b32 s29, s31, s43
	s_cselect_b32 vcc_lo, s30, s42
	s_ashr_i32 s37, s36, 31
	s_lshl_b64 s[4:5], s[36:37], 19
	s_add_u32 s34, s17, s4
	s_addc_u32 s35, s70, s5
	s_and_b64 s[4:5], s[40:41], exec
	s_cselect_b32 s37, s35, s39
	s_cselect_b32 vcc_hi, s34, s38
	s_add_u32 s59, s38, 0x100
	v_mov_b32_e32 v74, 0
	s_addc_u32 s72, s39, 0
	s_mov_b32 s73, -2
	s_add_u32 s38, s42, 0x100
	s_addc_u32 s39, s43, 0
	s_add_i32 s4, 0, 0x10000
	s_cmp_eq_u32 s73, 12
	s_cselect_b32 s69, s29, s39
	s_cselect_b32 s68, vcc_lo, s38
	s_cselect_b32 s67, s37, s72
	s_cselect_b32 s66, vcc_hi, s59
	s_add_i32 s6, 0, 0x14000
	v_add_u32_e32 v142, s4, v251
	v_add_u32_e32 v158, s6, v251
	ds_read_b128 v[130:133], v142
	ds_read_b128 v[134:137], v142 offset:1024
	ds_read_b128 v[138:141], v142 offset:2048
	ds_read_b128 v[142:145], v142 offset:3072
	ds_read_b128 v[146:149], v158
	ds_read_b128 v[150:153], v158 offset:1024
	ds_read_b128 v[154:157], v158 offset:2048
	ds_read_b128 v[158:161], v158 offset:3072
	v_lshl_add_u64 v[194:195], s[42:43], 0, v[228:229]
	s_add_i32 m0, s75, 0xc000
	ds_read_b128 v[162:165], v244
	ds_read_b128 v[166:169], v244 offset:1024
	ds_read_b128 v[170:173], v244 offset:2048
	ds_read_b128 v[174:177], v244 offset:3072
	ds_read_b128 v[178:181], v244 offset:4096
	ds_read_b128 v[182:185], v244 offset:5120
	ds_read_b128 v[186:189], v244 offset:6144
	ds_read_b128 v[190:193], v244 offset:7168
	global_load_lds_dwordx4 v[194:195], off
	v_lshl_add_u64 v[194:195], s[42:43], 0, v[230:231]
	s_add_i32 m0, s75, 0xe000
	s_nop 0
	global_load_lds_dwordx4 v[194:195], off
	s_waitcnt vmcnt(8)
	s_waitcnt lgkmcnt(0)
	s_barrier
	s_setprio 1
	s_waitcnt lgkmcnt(0)
	v_mfma_f32_16x16x32_bf16 v[114:117], v[130:133], v[162:165], 0
	v_mfma_f32_16x16x32_bf16 v[122:125], v[138:141], v[162:165], 0
	v_mfma_f32_16x16x32_bf16 v[118:121], v[130:133], v[170:173], 0
	v_mfma_f32_16x16x32_bf16 v[126:129], v[138:141], v[170:173], 0
	v_mfma_f32_16x16x32_bf16 v[54:57], v[130:133], v[178:181], 0
	v_mfma_f32_16x16x32_bf16 v[70:73], v[138:141], v[178:181], 0
	v_mfma_f32_16x16x32_bf16 v[50:53], v[130:133], v[186:189], 0
	v_mfma_f32_16x16x32_bf16 v[66:69], v[138:141], v[186:189], 0
	v_mfma_f32_16x16x32_bf16 v[114:117], v[134:137], v[166:169], v[114:117]
	v_mfma_f32_16x16x32_bf16 v[122:125], v[142:145], v[166:169], v[122:125]
	v_mfma_f32_16x16x32_bf16 v[118:121], v[134:137], v[174:177], v[118:121]
	v_mfma_f32_16x16x32_bf16 v[126:129], v[142:145], v[174:177], v[126:129]
	v_mfma_f32_16x16x32_bf16 v[54:57], v[134:137], v[182:185], v[54:57]
	v_mfma_f32_16x16x32_bf16 v[70:73], v[142:145], v[182:185], v[70:73]
	v_mfma_f32_16x16x32_bf16 v[50:53], v[134:137], v[190:193], v[50:53]
	v_mfma_f32_16x16x32_bf16 v[66:69], v[142:145], v[190:193], v[66:69]
	s_setprio 0
	s_setprio 1
	v_mfma_f32_16x16x32_bf16 v[106:109], v[146:149], v[162:165], 0
	v_mfma_f32_16x16x32_bf16 v[42:45], v[154:157], v[162:165], 0
	v_mfma_f32_16x16x32_bf16 v[110:113], v[146:149], v[170:173], 0
	v_mfma_f32_16x16x32_bf16 v[46:49], v[154:157], v[170:173], 0
	v_mfma_f32_16x16x32_bf16 v[30:33], v[146:149], v[178:181], 0
	v_mfma_f32_16x16x32_bf16 v[14:17], v[154:157], v[178:181], 0
	v_mfma_f32_16x16x32_bf16 v[26:29], v[146:149], v[186:189], 0
	v_mfma_f32_16x16x32_bf16 v[10:13], v[154:157], v[186:189], 0
	v_mfma_f32_16x16x32_bf16 v[106:109], v[150:153], v[166:169], v[106:109]
	v_mfma_f32_16x16x32_bf16 v[42:45], v[158:161], v[166:169], v[42:45]
	v_mfma_f32_16x16x32_bf16 v[110:113], v[150:153], v[174:177], v[110:113]
	v_mfma_f32_16x16x32_bf16 v[46:49], v[158:161], v[174:177], v[46:49]
	v_mfma_f32_16x16x32_bf16 v[30:33], v[150:153], v[182:185], v[30:33]
	v_mfma_f32_16x16x32_bf16 v[14:17], v[158:161], v[182:185], v[14:17]
	v_mfma_f32_16x16x32_bf16 v[26:29], v[150:153], v[190:193], v[26:29]
	s_barrier
	v_mfma_f32_16x16x32_bf16 v[10:13], v[158:161], v[190:193], v[10:13]
	s_setprio 0
	s_add_i32 s4, s4, s74
	v_lshl_add_u64 v[194:195], s[66:67], 0, v[0:1]
	s_mov_b32 m0, s4
	ds_read_b128 v[162:165], v244 offset:16384
	ds_read_b128 v[166:169], v244 offset:17408
	ds_read_b128 v[170:173], v244 offset:18432
	ds_read_b128 v[174:177], v244 offset:19456
	ds_read_b128 v[178:181], v244 offset:20480
	ds_read_b128 v[182:185], v244 offset:21504
	ds_read_b128 v[186:189], v244 offset:22528
	ds_read_b128 v[190:193], v244 offset:23552
	global_load_lds_dwordx4 v[194:195], off
	s_add_i32 m0, s4, 0x2000
	s_add_u32 s4, s66, 0x40000
	v_lshl_add_u64 v[196:197], s[66:67], 0, v[224:225]
	s_addc_u32 s5, s67, 0
	s_add_i32 s6, s6, s74
	global_load_lds_dwordx4 v[196:197], off
	v_lshl_add_u64 v[198:199], s[4:5], 0, v[0:1]
	s_mov_b32 m0, s6
	v_lshl_add_u64 v[200:201], s[68:69], 0, v[222:223]
	global_load_lds_dwordx4 v[198:199], off
	v_lshl_add_u64 v[198:199], s[4:5], 0, v[224:225]
	s_add_i32 m0, s6, 0x2000
	s_nop 0
	global_load_lds_dwordx4 v[198:199], off
	v_lshl_add_u64 v[198:199], s[68:69], 0, v[226:227]
	s_mov_b32 m0, s75
	s_nop 0
	global_load_lds_dwordx4 v[198:199], off
	s_mov_b32 m0, s76
	s_nop 0
	global_load_lds_dwordx4 v[200:201], off
	s_waitcnt vmcnt(8)
	s_waitcnt lgkmcnt(0)
	s_barrier
	s_setprio 1
	s_waitcnt lgkmcnt(0)
	v_mfma_f32_16x16x32_bf16 v[38:41], v[130:133], v[162:165], 0
	v_mfma_f32_16x16x32_bf16 v[62:65], v[138:141], v[162:165], 0
	v_mfma_f32_16x16x32_bf16 v[34:37], v[130:133], v[170:173], 0
	v_mfma_f32_16x16x32_bf16 v[58:61], v[138:141], v[170:173], 0
	v_mfma_f32_16x16x32_bf16 v[102:105], v[130:133], v[178:181], 0
	v_mfma_f32_16x16x32_bf16 v[98:101], v[138:141], v[178:181], 0
	v_mfma_f32_16x16x32_bf16 v[94:97], v[130:133], v[186:189], 0
	v_mfma_f32_16x16x32_bf16 v[90:93], v[138:141], v[186:189], 0
	v_mfma_f32_16x16x32_bf16 v[38:41], v[134:137], v[166:169], v[38:41]
	v_mfma_f32_16x16x32_bf16 v[62:65], v[142:145], v[166:169], v[62:65]
	v_mfma_f32_16x16x32_bf16 v[34:37], v[134:137], v[174:177], v[34:37]
	v_mfma_f32_16x16x32_bf16 v[58:61], v[142:145], v[174:177], v[58:61]
	v_mfma_f32_16x16x32_bf16 v[102:105], v[134:137], v[182:185], v[102:105]
	v_mfma_f32_16x16x32_bf16 v[98:101], v[142:145], v[182:185], v[98:101]
	v_mfma_f32_16x16x32_bf16 v[94:97], v[134:137], v[190:193], v[94:97]
	v_mfma_f32_16x16x32_bf16 v[90:93], v[142:145], v[190:193], v[90:93]
	s_setprio 0
	s_setprio 1
	v_mfma_f32_16x16x32_bf16 v[22:25], v[146:149], v[162:165], 0
	v_mfma_f32_16x16x32_bf16 v[6:9], v[154:157], v[162:165], 0
	v_mfma_f32_16x16x32_bf16 v[18:21], v[146:149], v[170:173], 0
	v_mfma_f32_16x16x32_bf16 v[2:5], v[154:157], v[170:173], 0
	v_mfma_f32_16x16x32_bf16 v[86:89], v[146:149], v[178:181], 0
	v_mfma_f32_16x16x32_bf16 v[82:85], v[154:157], v[178:181], 0
	v_mfma_f32_16x16x32_bf16 v[78:81], v[146:149], v[186:189], 0
	v_mfma_f32_16x16x32_bf16 v[74:77], v[154:157], v[186:189], 0
	v_mfma_f32_16x16x32_bf16 v[22:25], v[150:153], v[166:169], v[22:25]
	v_mfma_f32_16x16x32_bf16 v[6:9], v[158:161], v[166:169], v[6:9]
	v_mfma_f32_16x16x32_bf16 v[18:21], v[150:153], v[174:177], v[18:21]
	v_mfma_f32_16x16x32_bf16 v[2:5], v[158:161], v[174:177], v[2:5]
	v_mfma_f32_16x16x32_bf16 v[86:89], v[150:153], v[182:185], v[86:89]
	v_mfma_f32_16x16x32_bf16 v[82:85], v[158:161], v[182:185], v[82:85]
	v_mfma_f32_16x16x32_bf16 v[78:81], v[150:153], v[190:193], v[78:81]
	s_barrier
	v_mfma_f32_16x16x32_bf16 v[74:77], v[158:161], v[190:193], v[74:77]
	s_setprio 0
	s_add_i32 s6, 0, 0x18000
	s_add_i32 s7, 0, 0x1c000
	v_add_u32_e32 v142, s6, v251
	v_add_u32_e32 v158, s7, v251
	ds_read_b128 v[130:133], v142
	ds_read_b128 v[134:137], v142 offset:1024
	ds_read_b128 v[138:141], v142 offset:2048
	ds_read_b128 v[142:145], v142 offset:3072
	ds_read_b128 v[146:149], v158
	ds_read_b128 v[150:153], v158 offset:1024
	ds_read_b128 v[154:157], v158 offset:2048
	ds_read_b128 v[158:161], v158 offset:3072
	s_add_u32 s4, s68, 0x2000
	s_addc_u32 s5, s69, 0
	s_mov_b32 m0, s77
	v_lshl_add_u64 v[202:203], s[4:5], 0, v[226:227]
	ds_read_b128 v[162:165], v244 offset:32768
	ds_read_b128 v[166:169], v244 offset:33792
	ds_read_b128 v[170:173], v244 offset:34816
	ds_read_b128 v[174:177], v244 offset:35840
	ds_read_b128 v[178:181], v244 offset:36864
	ds_read_b128 v[182:185], v244 offset:37888
	ds_read_b128 v[186:189], v244 offset:38912
	ds_read_b128 v[190:193], v244 offset:39936
	global_load_lds_dwordx4 v[202:203], off
	v_lshl_add_u64 v[202:203], s[4:5], 0, v[222:223]
	s_mov_b32 m0, s78
	s_nop 0
	global_load_lds_dwordx4 v[202:203], off
	s_waitcnt vmcnt(8)
	s_waitcnt lgkmcnt(0)
	s_barrier
	s_setprio 1
	s_waitcnt lgkmcnt(0)
	v_mfma_f32_16x16x32_bf16 v[114:117], v[130:133], v[162:165], v[114:117]
	v_mfma_f32_16x16x32_bf16 v[122:125], v[138:141], v[162:165], v[122:125]
	v_mfma_f32_16x16x32_bf16 v[118:121], v[130:133], v[170:173], v[118:121]
	v_mfma_f32_16x16x32_bf16 v[126:129], v[138:141], v[170:173], v[126:129]
	v_mfma_f32_16x16x32_bf16 v[54:57], v[130:133], v[178:181], v[54:57]
	v_mfma_f32_16x16x32_bf16 v[70:73], v[138:141], v[178:181], v[70:73]
	v_mfma_f32_16x16x32_bf16 v[50:53], v[130:133], v[186:189], v[50:53]
	v_mfma_f32_16x16x32_bf16 v[66:69], v[138:141], v[186:189], v[66:69]
	v_mfma_f32_16x16x32_bf16 v[114:117], v[134:137], v[166:169], v[114:117]
	v_mfma_f32_16x16x32_bf16 v[122:125], v[142:145], v[166:169], v[122:125]
	v_mfma_f32_16x16x32_bf16 v[118:121], v[134:137], v[174:177], v[118:121]
	v_mfma_f32_16x16x32_bf16 v[126:129], v[142:145], v[174:177], v[126:129]
	v_mfma_f32_16x16x32_bf16 v[54:57], v[134:137], v[182:185], v[54:57]
	v_mfma_f32_16x16x32_bf16 v[70:73], v[142:145], v[182:185], v[70:73]
	v_mfma_f32_16x16x32_bf16 v[50:53], v[134:137], v[190:193], v[50:53]
	v_mfma_f32_16x16x32_bf16 v[66:69], v[142:145], v[190:193], v[66:69]
	s_setprio 0
	s_setprio 1
	v_mfma_f32_16x16x32_bf16 v[106:109], v[146:149], v[162:165], v[106:109]
	v_mfma_f32_16x16x32_bf16 v[42:45], v[154:157], v[162:165], v[42:45]
	v_mfma_f32_16x16x32_bf16 v[110:113], v[146:149], v[170:173], v[110:113]
	v_mfma_f32_16x16x32_bf16 v[46:49], v[154:157], v[170:173], v[46:49]
	v_mfma_f32_16x16x32_bf16 v[30:33], v[146:149], v[178:181], v[30:33]
	v_mfma_f32_16x16x32_bf16 v[14:17], v[154:157], v[178:181], v[14:17]
	v_mfma_f32_16x16x32_bf16 v[26:29], v[146:149], v[186:189], v[26:29]
	v_mfma_f32_16x16x32_bf16 v[10:13], v[154:157], v[186:189], v[10:13]
	v_mfma_f32_16x16x32_bf16 v[106:109], v[150:153], v[166:169], v[106:109]
	v_mfma_f32_16x16x32_bf16 v[42:45], v[158:161], v[166:169], v[42:45]
	v_mfma_f32_16x16x32_bf16 v[110:113], v[150:153], v[174:177], v[110:113]
	v_mfma_f32_16x16x32_bf16 v[46:49], v[158:161], v[174:177], v[46:49]
	v_mfma_f32_16x16x32_bf16 v[30:33], v[150:153], v[182:185], v[30:33]
	v_mfma_f32_16x16x32_bf16 v[14:17], v[158:161], v[182:185], v[14:17]
	v_mfma_f32_16x16x32_bf16 v[26:29], v[150:153], v[190:193], v[26:29]
	s_barrier
	v_mfma_f32_16x16x32_bf16 v[10:13], v[158:161], v[190:193], v[10:13]
	s_setprio 0
	s_add_i32 s4, s6, s74
	v_lshl_add_u64 v[194:195], v[194:195], 0, s[82:83]
	s_mov_b32 m0, s4
	ds_read_b128 v[162:165], v244 offset:49152
	ds_read_b128 v[166:169], v244 offset:50176
	ds_read_b128 v[170:173], v244 offset:51200
	ds_read_b128 v[174:177], v244 offset:52224
	ds_read_b128 v[178:181], v244 offset:53248
	ds_read_b128 v[182:185], v244 offset:54272
	ds_read_b128 v[186:189], v244 offset:55296
	ds_read_b128 v[190:193], v244 offset:56320
	global_load_lds_dwordx4 v[194:195], off
	s_add_i32 m0, s4, 0x2000
	s_add_u32 s4, s66, 0x40080
	v_lshl_add_u64 v[194:195], v[196:197], 0, s[82:83]
	s_addc_u32 s5, s67, 0
	s_add_i32 s6, s7, s74
	global_load_lds_dwordx4 v[194:195], off
	v_lshl_add_u64 v[194:195], s[4:5], 0, v[0:1]
	s_mov_b32 m0, s6
	s_nop 0
	global_load_lds_dwordx4 v[194:195], off
	v_lshl_add_u64 v[194:195], s[4:5], 0, v[224:225]
	s_add_i32 m0, s6, 0x2000
	s_nop 0
	global_load_lds_dwordx4 v[194:195], off
	v_lshl_add_u64 v[194:195], v[198:199], 0, s[82:83]
	s_mov_b32 m0, s94
	s_nop 0
	global_load_lds_dwordx4 v[194:195], off
	v_lshl_add_u64 v[194:195], v[200:201], 0, s[82:83]
	s_mov_b32 m0, s95
	s_nop 0
	global_load_lds_dwordx4 v[194:195], off
	s_waitcnt vmcnt(8)
	s_waitcnt lgkmcnt(0)
	s_barrier
	s_setprio 1
	s_waitcnt lgkmcnt(0)
	v_mfma_f32_16x16x32_bf16 v[38:41], v[130:133], v[162:165], v[38:41]
	v_mfma_f32_16x16x32_bf16 v[62:65], v[138:141], v[162:165], v[62:65]
	v_mfma_f32_16x16x32_bf16 v[34:37], v[130:133], v[170:173], v[34:37]
	v_mfma_f32_16x16x32_bf16 v[58:61], v[138:141], v[170:173], v[58:61]
	v_mfma_f32_16x16x32_bf16 v[102:105], v[130:133], v[178:181], v[102:105]
	v_mfma_f32_16x16x32_bf16 v[98:101], v[138:141], v[178:181], v[98:101]
	v_mfma_f32_16x16x32_bf16 v[94:97], v[130:133], v[186:189], v[94:97]
	v_mfma_f32_16x16x32_bf16 v[90:93], v[138:141], v[186:189], v[90:93]
	v_mfma_f32_16x16x32_bf16 v[38:41], v[134:137], v[166:169], v[38:41]
	v_mfma_f32_16x16x32_bf16 v[62:65], v[142:145], v[166:169], v[62:65]
	v_mfma_f32_16x16x32_bf16 v[34:37], v[134:137], v[174:177], v[34:37]
	v_mfma_f32_16x16x32_bf16 v[58:61], v[142:145], v[174:177], v[58:61]
	v_mfma_f32_16x16x32_bf16 v[102:105], v[134:137], v[182:185], v[102:105]
	v_mfma_f32_16x16x32_bf16 v[98:101], v[142:145], v[182:185], v[98:101]
	v_mfma_f32_16x16x32_bf16 v[94:97], v[134:137], v[190:193], v[94:97]
	v_mfma_f32_16x16x32_bf16 v[90:93], v[142:145], v[190:193], v[90:93]
	s_setprio 0
	s_setprio 1
	v_mfma_f32_16x16x32_bf16 v[22:25], v[146:149], v[162:165], v[22:25]
	v_mfma_f32_16x16x32_bf16 v[6:9], v[154:157], v[162:165], v[6:9]
	v_mfma_f32_16x16x32_bf16 v[18:21], v[146:149], v[170:173], v[18:21]
	v_mfma_f32_16x16x32_bf16 v[2:5], v[154:157], v[170:173], v[2:5]
	v_mfma_f32_16x16x32_bf16 v[86:89], v[146:149], v[178:181], v[86:89]
	v_mfma_f32_16x16x32_bf16 v[82:85], v[154:157], v[178:181], v[82:85]
	v_mfma_f32_16x16x32_bf16 v[78:81], v[146:149], v[186:189], v[78:81]
	v_mfma_f32_16x16x32_bf16 v[74:77], v[154:157], v[186:189], v[74:77]
	v_mfma_f32_16x16x32_bf16 v[22:25], v[150:153], v[166:169], v[22:25]
	v_mfma_f32_16x16x32_bf16 v[6:9], v[158:161], v[166:169], v[6:9]
	v_mfma_f32_16x16x32_bf16 v[18:21], v[150:153], v[174:177], v[18:21]
	v_mfma_f32_16x16x32_bf16 v[2:5], v[158:161], v[174:177], v[2:5]
	v_mfma_f32_16x16x32_bf16 v[86:89], v[150:153], v[182:185], v[86:89]
	v_mfma_f32_16x16x32_bf16 v[82:85], v[158:161], v[182:185], v[82:85]
	v_mfma_f32_16x16x32_bf16 v[78:81], v[150:153], v[190:193], v[78:81]
	s_barrier
	v_mfma_f32_16x16x32_bf16 v[74:77], v[158:161], v[190:193], v[74:77]
	s_setprio 0
	s_add_i32 s73, s73, 2
	s_add_u32 s59, s59, 0x100
	s_addc_u32 s72, s72, 0
	s_cmp_gt_u32 s73, 13
	s_mov_b64 s[42:43], s[38:39]

.LBB0_451:
	s_add_u32 s30, s30, 0x80
	s_addc_u32 s31, s31, 0
	s_add_u32 s42, s34, 0x100
	v_mov_b32_e32 v2, 0
	s_addc_u32 s43, s35, 0
	s_mov_b32 s34, 0
	s_waitcnt lgkmcnt(0)
	s_add_i32 s59, s34, 2
	s_add_u32 s4, s30, 0x80
	s_addc_u32 s5, s31, 0
	s_add_i32 s6, 0, 0x10000
	s_cmp_eq_u32 s53, s34
	s_cselect_b32 s35, s27, s5
	s_cselect_b32 s34, s26, s4
	s_cselect_b32 s5, s29, s43
	s_cselect_b32 s4, s28, s42
	s_add_i32 s7, 0, 0x14000
	v_add_u32_e32 v142, s6, v184
	v_add_u32_e32 v168, s7, v184
	ds_read_b128 v[130:133], v142
	ds_read_b128 v[134:137], v142 offset:1024
	ds_read_b128 v[138:141], v142 offset:2048
	ds_read_b128 v[142:145], v142 offset:3072
	ds_read_b128 v[146:149], v168
	ds_read_b128 v[150:153], v168 offset:1024
	ds_read_b128 v[154:157], v168 offset:2048
	ds_read_b128 v[168:171], v168 offset:3072
	v_lshl_add_u64 v[180:181], s[30:31], 0, v[164:165]
	s_add_i32 m0, s38, 0xc000
	ds_read_b128 v[172:175], v187
	ds_read_b128 v[176:179], v187 offset:1024
	ds_read_b128 v[188:191], v187 offset:2048
	ds_read_b128 v[192:195], v187 offset:3072
	ds_read_b128 v[196:199], v187 offset:4096
	ds_read_b128 v[200:203], v187 offset:5120
	ds_read_b128 v[204:207], v187 offset:6144
	ds_read_b128 v[222:225], v187 offset:7168
	global_load_lds_dwordx4 v[180:181], off
	v_lshl_add_u64 v[180:181], s[30:31], 0, v[166:167]
	s_add_i32 m0, s38, 0xe000
	s_nop 0
	global_load_lds_dwordx4 v[180:181], off
	s_waitcnt vmcnt(8)
	s_waitcnt lgkmcnt(0)
	s_barrier
	s_setprio 1
	s_waitcnt lgkmcnt(0)
	v_mfma_f32_16x16x32_bf16 v[126:129], v[130:133], v[172:175], 0
	v_mfma_f32_16x16x32_bf16 v[122:125], v[138:141], v[172:175], 0
	v_mfma_f32_16x16x32_bf16 v[110:113], v[130:133], v[188:191], 0
	v_mfma_f32_16x16x32_bf16 v[106:109], v[138:141], v[188:191], 0
	v_mfma_f32_16x16x32_bf16 v[98:101], v[130:133], v[196:199], 0
	v_mfma_f32_16x16x32_bf16 v[90:93], v[138:141], v[196:199], 0
	v_mfma_f32_16x16x32_bf16 v[82:85], v[130:133], v[204:207], 0
	v_mfma_f32_16x16x32_bf16 v[74:77], v[138:141], v[204:207], 0
	v_mfma_f32_16x16x32_bf16 v[126:129], v[134:137], v[176:179], v[126:129]
	v_mfma_f32_16x16x32_bf16 v[122:125], v[142:145], v[176:179], v[122:125]
	v_mfma_f32_16x16x32_bf16 v[110:113], v[134:137], v[192:195], v[110:113]
	v_mfma_f32_16x16x32_bf16 v[106:109], v[142:145], v[192:195], v[106:109]
	v_mfma_f32_16x16x32_bf16 v[98:101], v[134:137], v[200:203], v[98:101]
	v_mfma_f32_16x16x32_bf16 v[90:93], v[142:145], v[200:203], v[90:93]
	v_mfma_f32_16x16x32_bf16 v[82:85], v[134:137], v[222:225], v[82:85]
	v_mfma_f32_16x16x32_bf16 v[74:77], v[142:145], v[222:225], v[74:77]
	s_setprio 0
	s_setprio 1
	v_mfma_f32_16x16x32_bf16 v[118:121], v[146:149], v[172:175], 0
	v_mfma_f32_16x16x32_bf16 v[114:117], v[154:157], v[172:175], 0
	v_mfma_f32_16x16x32_bf16 v[102:105], v[146:149], v[188:191], 0
	v_mfma_f32_16x16x32_bf16 v[94:97], v[154:157], v[188:191], 0
	v_mfma_f32_16x16x32_bf16 v[86:89], v[146:149], v[196:199], 0
	v_mfma_f32_16x16x32_bf16 v[78:81], v[154:157], v[196:199], 0
	v_mfma_f32_16x16x32_bf16 v[70:73], v[146:149], v[204:207], 0
	v_mfma_f32_16x16x32_bf16 v[66:69], v[154:157], v[204:207], 0
	v_mfma_f32_16x16x32_bf16 v[118:121], v[150:153], v[176:179], v[118:121]
	v_mfma_f32_16x16x32_bf16 v[114:117], v[168:171], v[176:179], v[114:117]
	v_mfma_f32_16x16x32_bf16 v[102:105], v[150:153], v[192:195], v[102:105]
	v_mfma_f32_16x16x32_bf16 v[94:97], v[168:171], v[192:195], v[94:97]
	v_mfma_f32_16x16x32_bf16 v[86:89], v[150:153], v[200:203], v[86:89]
	v_mfma_f32_16x16x32_bf16 v[78:81], v[168:171], v[200:203], v[78:81]
	v_mfma_f32_16x16x32_bf16 v[70:73], v[150:153], v[222:225], v[70:73]
	s_barrier
	v_mfma_f32_16x16x32_bf16 v[66:69], v[168:171], v[222:225], v[66:69]
	s_setprio 0
	s_add_i32 s6, s6, s37
	v_lshl_add_u64 v[180:181], s[4:5], 0, v[0:1]
	s_mov_b32 m0, s6
	ds_read_b128 v[172:175], v187 offset:16384
	ds_read_b128 v[176:179], v187 offset:17408
	ds_read_b128 v[188:191], v187 offset:18432
	ds_read_b128 v[192:195], v187 offset:19456
	ds_read_b128 v[196:199], v187 offset:20480
	ds_read_b128 v[200:203], v187 offset:21504
	ds_read_b128 v[204:207], v187 offset:22528
	ds_read_b128 v[222:225], v187 offset:23552
	global_load_lds_dwordx4 v[180:181], off
	s_add_i32 m0, s6, 0x2000
	v_lshl_add_u64 v[208:209], s[4:5], 0, v[160:161]
	s_add_u32 s4, s4, s84
	s_addc_u32 s5, s5, 0
	s_add_i32 s6, s7, s37
	global_load_lds_dwordx4 v[208:209], off
	v_lshl_add_u64 v[226:227], s[4:5], 0, v[0:1]
	s_mov_b32 m0, s6
	v_lshl_add_u64 v[228:229], s[4:5], 0, v[160:161]
	global_load_lds_dwordx4 v[226:227], off
	s_add_i32 m0, s6, 0x2000
	v_lshl_add_u64 v[230:231], s[34:35], 0, v[162:163]
	global_load_lds_dwordx4 v[228:229], off
	s_mov_b32 m0, s38
	v_lshl_add_u64 v[232:233], s[34:35], 0, v[158:159]
	global_load_lds_dwordx4 v[230:231], off
	s_mov_b32 m0, s39
	s_nop 0
	global_load_lds_dwordx4 v[232:233], off
	s_waitcnt vmcnt(8)
	s_waitcnt lgkmcnt(0)
	s_barrier
	s_setprio 1
	s_waitcnt lgkmcnt(0)
	v_mfma_f32_16x16x32_bf16 v[62:65], v[130:133], v[172:175], 0
	v_mfma_f32_16x16x32_bf16 v[58:61], v[138:141], v[172:175], 0
	v_mfma_f32_16x16x32_bf16 v[46:49], v[130:133], v[188:191], 0
	v_mfma_f32_16x16x32_bf16 v[42:45], v[138:141], v[188:191], 0
	v_mfma_f32_16x16x32_bf16 v[34:37], v[130:133], v[196:199], 0
	v_mfma_f32_16x16x32_bf16 v[26:29], v[138:141], v[196:199], 0
	v_mfma_f32_16x16x32_bf16 v[18:21], v[130:133], v[204:207], 0
	v_mfma_f32_16x16x32_bf16 v[10:13], v[138:141], v[204:207], 0
	v_mfma_f32_16x16x32_bf16 v[62:65], v[134:137], v[176:179], v[62:65]
	v_mfma_f32_16x16x32_bf16 v[58:61], v[142:145], v[176:179], v[58:61]
	v_mfma_f32_16x16x32_bf16 v[46:49], v[134:137], v[192:195], v[46:49]
	v_mfma_f32_16x16x32_bf16 v[42:45], v[142:145], v[192:195], v[42:45]
	v_mfma_f32_16x16x32_bf16 v[34:37], v[134:137], v[200:203], v[34:37]
	v_mfma_f32_16x16x32_bf16 v[26:29], v[142:145], v[200:203], v[26:29]
	v_mfma_f32_16x16x32_bf16 v[18:21], v[134:137], v[222:225], v[18:21]
	v_mfma_f32_16x16x32_bf16 v[10:13], v[142:145], v[222:225], v[10:13]
	s_setprio 0
	s_setprio 1
	v_mfma_f32_16x16x32_bf16 v[54:57], v[146:149], v[172:175], 0
	v_mfma_f32_16x16x32_bf16 v[50:53], v[154:157], v[172:175], 0
	v_mfma_f32_16x16x32_bf16 v[38:41], v[146:149], v[188:191], 0
	v_mfma_f32_16x16x32_bf16 v[30:33], v[154:157], v[188:191], 0
	v_mfma_f32_16x16x32_bf16 v[22:25], v[146:149], v[196:199], 0
	v_mfma_f32_16x16x32_bf16 v[14:17], v[154:157], v[196:199], 0
	v_mfma_f32_16x16x32_bf16 v[6:9], v[146:149], v[204:207], 0
	v_mfma_f32_16x16x32_bf16 v[2:5], v[154:157], v[204:207], 0
	v_mfma_f32_16x16x32_bf16 v[54:57], v[150:153], v[176:179], v[54:57]
	v_mfma_f32_16x16x32_bf16 v[50:53], v[168:171], v[176:179], v[50:53]
	v_mfma_f32_16x16x32_bf16 v[38:41], v[150:153], v[192:195], v[38:41]
	v_mfma_f32_16x16x32_bf16 v[30:33], v[168:171], v[192:195], v[30:33]
	v_mfma_f32_16x16x32_bf16 v[22:25], v[150:153], v[200:203], v[22:25]
	v_mfma_f32_16x16x32_bf16 v[14:17], v[168:171], v[200:203], v[14:17]
	v_mfma_f32_16x16x32_bf16 v[6:9], v[150:153], v[222:225], v[6:9]
	s_barrier
	v_mfma_f32_16x16x32_bf16 v[2:5], v[168:171], v[222:225], v[2:5]
	s_setprio 0
	s_add_i32 s6, 0, 0x18000
	s_add_i32 s7, 0, 0x1c000
	v_add_u32_e32 v142, s6, v184
	v_add_u32_e32 v168, s7, v184
	ds_read_b128 v[130:133], v142
	ds_read_b128 v[134:137], v142 offset:1024
	ds_read_b128 v[138:141], v142 offset:2048
	ds_read_b128 v[142:145], v142 offset:3072
	ds_read_b128 v[146:149], v168
	ds_read_b128 v[150:153], v168 offset:1024
	ds_read_b128 v[154:157], v168 offset:2048
	ds_read_b128 v[168:171], v168 offset:3072
	s_add_u32 s4, s34, s84
	s_addc_u32 s5, s35, 0
	s_mov_b32 m0, s45
	v_lshl_add_u64 v[234:235], s[4:5], 0, v[162:163]
	ds_read_b128 v[172:175], v187 offset:32768
	ds_read_b128 v[176:179], v187 offset:33792
	ds_read_b128 v[188:191], v187 offset:34816
	ds_read_b128 v[192:195], v187 offset:35840
	ds_read_b128 v[196:199], v187 offset:36864
	ds_read_b128 v[200:203], v187 offset:37888
	ds_read_b128 v[204:207], v187 offset:38912
	ds_read_b128 v[222:225], v187 offset:39936
	global_load_lds_dwordx4 v[234:235], off
	v_lshl_add_u64 v[234:235], s[4:5], 0, v[158:159]
	s_mov_b32 m0, s46
	s_nop 0
	global_load_lds_dwordx4 v[234:235], off
	s_waitcnt vmcnt(8)
	s_waitcnt lgkmcnt(0)
	s_barrier
	s_setprio 1
	s_waitcnt lgkmcnt(0)
	v_mfma_f32_16x16x32_bf16 v[126:129], v[130:133], v[172:175], v[126:129]
	v_mfma_f32_16x16x32_bf16 v[122:125], v[138:141], v[172:175], v[122:125]
	v_mfma_f32_16x16x32_bf16 v[110:113], v[130:133], v[188:191], v[110:113]
	v_mfma_f32_16x16x32_bf16 v[106:109], v[138:141], v[188:191], v[106:109]
	v_mfma_f32_16x16x32_bf16 v[98:101], v[130:133], v[196:199], v[98:101]
	v_mfma_f32_16x16x32_bf16 v[90:93], v[138:141], v[196:199], v[90:93]
	v_mfma_f32_16x16x32_bf16 v[82:85], v[130:133], v[204:207], v[82:85]
	v_mfma_f32_16x16x32_bf16 v[74:77], v[138:141], v[204:207], v[74:77]
	v_mfma_f32_16x16x32_bf16 v[126:129], v[134:137], v[176:179], v[126:129]
	v_mfma_f32_16x16x32_bf16 v[122:125], v[142:145], v[176:179], v[122:125]
	v_mfma_f32_16x16x32_bf16 v[110:113], v[134:137], v[192:195], v[110:113]
	v_mfma_f32_16x16x32_bf16 v[106:109], v[142:145], v[192:195], v[106:109]
	v_mfma_f32_16x16x32_bf16 v[98:101], v[134:137], v[200:203], v[98:101]
	v_mfma_f32_16x16x32_bf16 v[90:93], v[142:145], v[200:203], v[90:93]
	v_mfma_f32_16x16x32_bf16 v[82:85], v[134:137], v[222:225], v[82:85]
	v_mfma_f32_16x16x32_bf16 v[74:77], v[142:145], v[222:225], v[74:77]
	s_setprio 0
	s_setprio 1
	v_mfma_f32_16x16x32_bf16 v[118:121], v[146:149], v[172:175], v[118:121]
	v_mfma_f32_16x16x32_bf16 v[114:117], v[154:157], v[172:175], v[114:117]
	v_mfma_f32_16x16x32_bf16 v[102:105], v[146:149], v[188:191], v[102:105]
	v_mfma_f32_16x16x32_bf16 v[94:97], v[154:157], v[188:191], v[94:97]
	v_mfma_f32_16x16x32_bf16 v[86:89], v[146:149], v[196:199], v[86:89]
	v_mfma_f32_16x16x32_bf16 v[78:81], v[154:157], v[196:199], v[78:81]
	v_mfma_f32_16x16x32_bf16 v[70:73], v[146:149], v[204:207], v[70:73]
	v_mfma_f32_16x16x32_bf16 v[66:69], v[154:157], v[204:207], v[66:69]
	v_mfma_f32_16x16x32_bf16 v[118:121], v[150:153], v[176:179], v[118:121]
	v_mfma_f32_16x16x32_bf16 v[114:117], v[168:171], v[176:179], v[114:117]
	v_mfma_f32_16x16x32_bf16 v[102:105], v[150:153], v[192:195], v[102:105]
	v_mfma_f32_16x16x32_bf16 v[94:97], v[168:171], v[192:195], v[94:97]
	v_mfma_f32_16x16x32_bf16 v[86:89], v[150:153], v[200:203], v[86:89]
	v_mfma_f32_16x16x32_bf16 v[78:81], v[168:171], v[200:203], v[78:81]
	v_mfma_f32_16x16x32_bf16 v[70:73], v[150:153], v[222:225], v[70:73]
	s_barrier
	v_mfma_f32_16x16x32_bf16 v[66:69], v[168:171], v[222:225], v[66:69]
	s_setprio 0
	s_add_i32 s4, s6, s37
	v_lshl_add_u64 v[180:181], v[180:181], 0, s[82:83]
	s_mov_b32 m0, s4
	ds_read_b128 v[172:175], v187 offset:49152
	ds_read_b128 v[176:179], v187 offset:50176
	ds_read_b128 v[188:191], v187 offset:51200
	ds_read_b128 v[192:195], v187 offset:52224
	ds_read_b128 v[196:199], v187 offset:53248
	ds_read_b128 v[200:203], v187 offset:54272
	ds_read_b128 v[204:207], v187 offset:55296
	ds_read_b128 v[222:225], v187 offset:56320
	global_load_lds_dwordx4 v[180:181], off
	v_lshl_add_u64 v[180:181], v[208:209], 0, s[82:83]
	s_add_i32 m0, s4, 0x2000
	s_add_i32 s4, s7, s37
	global_load_lds_dwordx4 v[180:181], off
	v_lshl_add_u64 v[180:181], v[226:227], 0, s[82:83]
	s_mov_b32 m0, s4
	s_nop 0
	global_load_lds_dwordx4 v[180:181], off
	v_lshl_add_u64 v[180:181], v[228:229], 0, s[82:83]
	s_add_i32 m0, s4, 0x2000
	s_nop 0
	global_load_lds_dwordx4 v[180:181], off
	v_lshl_add_u64 v[180:181], v[230:231], 0, s[82:83]
	s_mov_b32 m0, s51
	s_nop 0
	global_load_lds_dwordx4 v[180:181], off
	v_lshl_add_u64 v[180:181], v[232:233], 0, s[82:83]
	s_mov_b32 m0, s52
	s_nop 0
	global_load_lds_dwordx4 v[180:181], off
	s_waitcnt vmcnt(8)
	s_waitcnt lgkmcnt(0)
	s_barrier
	s_setprio 1
	s_waitcnt lgkmcnt(0)
	v_mfma_f32_16x16x32_bf16 v[62:65], v[130:133], v[172:175], v[62:65]
	v_mfma_f32_16x16x32_bf16 v[58:61], v[138:141], v[172:175], v[58:61]
	v_mfma_f32_16x16x32_bf16 v[46:49], v[130:133], v[188:191], v[46:49]
	v_mfma_f32_16x16x32_bf16 v[42:45], v[138:141], v[188:191], v[42:45]
	v_mfma_f32_16x16x32_bf16 v[34:37], v[130:133], v[196:199], v[34:37]
	v_mfma_f32_16x16x32_bf16 v[26:29], v[138:141], v[196:199], v[26:29]
	v_mfma_f32_16x16x32_bf16 v[18:21], v[130:133], v[204:207], v[18:21]
	v_mfma_f32_16x16x32_bf16 v[10:13], v[138:141], v[204:207], v[10:13]
	v_mfma_f32_16x16x32_bf16 v[62:65], v[134:137], v[176:179], v[62:65]
	v_mfma_f32_16x16x32_bf16 v[58:61], v[142:145], v[176:179], v[58:61]
	v_mfma_f32_16x16x32_bf16 v[46:49], v[134:137], v[192:195], v[46:49]
	v_mfma_f32_16x16x32_bf16 v[42:45], v[142:145], v[192:195], v[42:45]
	v_mfma_f32_16x16x32_bf16 v[34:37], v[134:137], v[200:203], v[34:37]
	v_mfma_f32_16x16x32_bf16 v[26:29], v[142:145], v[200:203], v[26:29]
	v_mfma_f32_16x16x32_bf16 v[18:21], v[134:137], v[222:225], v[18:21]
	v_mfma_f32_16x16x32_bf16 v[10:13], v[142:145], v[222:225], v[10:13]
	s_setprio 0
	s_setprio 1
	v_mfma_f32_16x16x32_bf16 v[54:57], v[146:149], v[172:175], v[54:57]
	v_mfma_f32_16x16x32_bf16 v[50:53], v[154:157], v[172:175], v[50:53]
	v_mfma_f32_16x16x32_bf16 v[38:41], v[146:149], v[188:191], v[38:41]
	v_mfma_f32_16x16x32_bf16 v[30:33], v[154:157], v[188:191], v[30:33]
	v_mfma_f32_16x16x32_bf16 v[22:25], v[146:149], v[196:199], v[22:25]
	v_mfma_f32_16x16x32_bf16 v[14:17], v[154:157], v[196:199], v[14:17]
	v_mfma_f32_16x16x32_bf16 v[6:9], v[146:149], v[204:207], v[6:9]
	v_mfma_f32_16x16x32_bf16 v[2:5], v[154:157], v[204:207], v[2:5]
	v_mfma_f32_16x16x32_bf16 v[54:57], v[150:153], v[176:179], v[54:57]
	v_mfma_f32_16x16x32_bf16 v[50:53], v[168:171], v[176:179], v[50:53]
	v_mfma_f32_16x16x32_bf16 v[38:41], v[150:153], v[192:195], v[38:41]
	v_mfma_f32_16x16x32_bf16 v[30:33], v[168:171], v[192:195], v[30:33]
	v_mfma_f32_16x16x32_bf16 v[22:25], v[150:153], v[200:203], v[22:25]
	v_mfma_f32_16x16x32_bf16 v[14:17], v[168:171], v[200:203], v[14:17]
	v_mfma_f32_16x16x32_bf16 v[6:9], v[150:153], v[222:225], v[6:9]
	s_barrier
	v_mfma_f32_16x16x32_bf16 v[2:5], v[168:171], v[222:225], v[2:5]
	s_setprio 0
	s_add_u32 s30, s30, 0x100
	s_addc_u32 s31, s31, 0
	s_add_u32 s42, s42, 0x100
	s_addc_u32 s43, s43, 0
	s_cmp_ge_u32 s59, s48
	s_mov_b32 s34, s59

.LBB0_488:
	s_ashr_i32 s25, s24, 31
	s_lshl_b64 s[4:5], s[24:25], 19
	s_add_u32 s26, s12, s4
	s_addc_u32 s27, s13, s5
	s_and_b64 s[4:5], s[40:41], exec
	s_cselect_b32 s25, s27, s31
	s_cselect_b32 s66, s26, s30
	s_ashr_i32 s23, s22, 31
	s_lshl_b64 s[4:5], s[22:23], 19
	s_add_u32 s28, s39, s4
	s_addc_u32 s29, s42, s5
	s_and_b64 s[4:5], s[40:41], exec
	s_cselect_b32 s23, s29, s35
	s_cselect_b32 s67, s28, s34
	s_add_u32 s30, s30, 0x40080
	s_addc_u32 s31, s31, 0
	s_add_u32 s68, s34, 0x100
	v_mov_b32_e32 v2, 0
	s_addc_u32 s69, s35, 0
	s_mov_b32 s59, -2
	s_add_u32 s4, s30, 0xfffc0080
	s_addc_u32 s5, s31, -1
	s_add_i32 s6, 0, 0x10000
	s_cmp_eq_u32 s59, 12
	s_cselect_b32 s37, s25, s5
	s_cselect_b32 s36, s66, s4
	s_cselect_b32 s35, s23, s69
	s_cselect_b32 s34, s67, s68
	s_add_i32 s7, 0, 0x14000
	v_add_u32_e32 v156, s6, v146
	v_add_u32_e32 v172, s7, v146
	ds_read_b128 v[140:143], v156
	ds_read_b128 v[148:151], v156 offset:1024
	ds_read_b128 v[152:155], v156 offset:2048
	ds_read_b128 v[156:159], v156 offset:3072
	ds_read_b128 v[160:163], v172
	ds_read_b128 v[164:167], v172 offset:1024
	ds_read_b128 v[168:171], v172 offset:2048
	ds_read_b128 v[172:175], v172 offset:3072
	v_lshl_add_u64 v[208:209], s[30:31], 0, v[136:137]
	s_add_i32 m0, s43, 0xc000
	ds_read_b128 v[176:179], v147
	ds_read_b128 v[180:183], v147 offset:1024
	ds_read_b128 v[184:187], v147 offset:2048
	ds_read_b128 v[188:191], v147 offset:3072
	ds_read_b128 v[192:195], v147 offset:4096
	ds_read_b128 v[196:199], v147 offset:5120
	ds_read_b128 v[200:203], v147 offset:6144
	ds_read_b128 v[204:207], v147 offset:7168
	global_load_lds_dwordx4 v[208:209], off
	v_lshl_add_u64 v[208:209], s[30:31], 0, v[138:139]
	s_add_i32 m0, s43, 0xe000
	s_nop 0
	global_load_lds_dwordx4 v[208:209], off
	s_waitcnt vmcnt(8)
	s_waitcnt lgkmcnt(0)
	s_barrier
	s_setprio 1
	s_waitcnt lgkmcnt(0)
	v_mfma_f32_16x16x32_bf16 v[126:129], v[140:143], v[176:179], 0
	v_mfma_f32_16x16x32_bf16 v[122:125], v[152:155], v[176:179], 0
	v_mfma_f32_16x16x32_bf16 v[118:121], v[140:143], v[184:187], 0
	v_mfma_f32_16x16x32_bf16 v[110:113], v[152:155], v[184:187], 0
	v_mfma_f32_16x16x32_bf16 v[102:105], v[140:143], v[192:195], 0
	v_mfma_f32_16x16x32_bf16 v[94:97], v[152:155], v[192:195], 0
	v_mfma_f32_16x16x32_bf16 v[86:89], v[140:143], v[200:203], 0
	v_mfma_f32_16x16x32_bf16 v[78:81], v[152:155], v[200:203], 0
	v_mfma_f32_16x16x32_bf16 v[126:129], v[148:151], v[180:183], v[126:129]
	v_mfma_f32_16x16x32_bf16 v[122:125], v[156:159], v[180:183], v[122:125]
	v_mfma_f32_16x16x32_bf16 v[118:121], v[148:151], v[188:191], v[118:121]
	v_mfma_f32_16x16x32_bf16 v[110:113], v[156:159], v[188:191], v[110:113]
	v_mfma_f32_16x16x32_bf16 v[102:105], v[148:151], v[196:199], v[102:105]
	v_mfma_f32_16x16x32_bf16 v[94:97], v[156:159], v[196:199], v[94:97]
	v_mfma_f32_16x16x32_bf16 v[86:89], v[148:151], v[204:207], v[86:89]
	v_mfma_f32_16x16x32_bf16 v[78:81], v[156:159], v[204:207], v[78:81]
	s_setprio 0
	s_setprio 1
	v_mfma_f32_16x16x32_bf16 v[114:117], v[160:163], v[176:179], 0
	v_mfma_f32_16x16x32_bf16 v[106:109], v[168:171], v[176:179], 0
	v_mfma_f32_16x16x32_bf16 v[98:101], v[160:163], v[184:187], 0
	v_mfma_f32_16x16x32_bf16 v[90:93], v[168:171], v[184:187], 0
	v_mfma_f32_16x16x32_bf16 v[82:85], v[160:163], v[192:195], 0
	v_mfma_f32_16x16x32_bf16 v[74:77], v[168:171], v[192:195], 0
	v_mfma_f32_16x16x32_bf16 v[70:73], v[160:163], v[200:203], 0
	v_mfma_f32_16x16x32_bf16 v[66:69], v[168:171], v[200:203], 0
	v_mfma_f32_16x16x32_bf16 v[114:117], v[164:167], v[180:183], v[114:117]
	v_mfma_f32_16x16x32_bf16 v[106:109], v[172:175], v[180:183], v[106:109]
	v_mfma_f32_16x16x32_bf16 v[98:101], v[164:167], v[188:191], v[98:101]
	v_mfma_f32_16x16x32_bf16 v[90:93], v[172:175], v[188:191], v[90:93]
	v_mfma_f32_16x16x32_bf16 v[82:85], v[164:167], v[196:199], v[82:85]
	v_mfma_f32_16x16x32_bf16 v[74:77], v[172:175], v[196:199], v[74:77]
	v_mfma_f32_16x16x32_bf16 v[70:73], v[164:167], v[204:207], v[70:73]
	s_barrier
	v_mfma_f32_16x16x32_bf16 v[66:69], v[172:175], v[204:207], v[66:69]
	s_setprio 0
	s_add_i32 s4, s6, s38
	v_lshl_add_u64 v[208:209], s[34:35], 0, v[0:1]
	s_mov_b32 m0, s4
	ds_read_b128 v[176:179], v147 offset:16384
	ds_read_b128 v[180:183], v147 offset:17408
	ds_read_b128 v[184:187], v147 offset:18432
	ds_read_b128 v[188:191], v147 offset:19456
	ds_read_b128 v[192:195], v147 offset:20480
	ds_read_b128 v[196:199], v147 offset:21504
	ds_read_b128 v[200:203], v147 offset:22528
	ds_read_b128 v[204:207], v147 offset:23552
	global_load_lds_dwordx4 v[208:209], off
	s_add_i32 m0, s4, 0x2000
	s_add_u32 s4, s34, 0x40000
	v_lshl_add_u64 v[222:223], s[34:35], 0, v[132:133]
	s_addc_u32 s5, s35, 0
	s_add_i32 s6, s7, s38
	global_load_lds_dwordx4 v[222:223], off
	v_lshl_add_u64 v[224:225], s[4:5], 0, v[0:1]
	s_mov_b32 m0, s6
	v_lshl_add_u64 v[226:227], s[36:37], 0, v[130:131]
	global_load_lds_dwordx4 v[224:225], off
	v_lshl_add_u64 v[224:225], s[4:5], 0, v[132:133]
	s_add_i32 m0, s6, 0x2000
	s_nop 0
	global_load_lds_dwordx4 v[224:225], off
	v_lshl_add_u64 v[224:225], s[36:37], 0, v[134:135]
	s_mov_b32 m0, s43
	s_nop 0
	global_load_lds_dwordx4 v[224:225], off
	s_mov_b32 m0, s44
	s_nop 0
	global_load_lds_dwordx4 v[226:227], off
	s_waitcnt vmcnt(8)
	s_waitcnt lgkmcnt(0)
	s_barrier
	s_setprio 1
	s_waitcnt lgkmcnt(0)
	v_mfma_f32_16x16x32_bf16 v[62:65], v[140:143], v[176:179], 0
	v_mfma_f32_16x16x32_bf16 v[58:61], v[152:155], v[176:179], 0
	v_mfma_f32_16x16x32_bf16 v[54:57], v[140:143], v[184:187], 0
	v_mfma_f32_16x16x32_bf16 v[46:49], v[152:155], v[184:187], 0
	v_mfma_f32_16x16x32_bf16 v[38:41], v[140:143], v[192:195], 0
	v_mfma_f32_16x16x32_bf16 v[30:33], v[152:155], v[192:195], 0
	v_mfma_f32_16x16x32_bf16 v[22:25], v[140:143], v[200:203], 0
	v_mfma_f32_16x16x32_bf16 v[14:17], v[152:155], v[200:203], 0
	v_mfma_f32_16x16x32_bf16 v[62:65], v[148:151], v[180:183], v[62:65]
	v_mfma_f32_16x16x32_bf16 v[58:61], v[156:159], v[180:183], v[58:61]
	v_mfma_f32_16x16x32_bf16 v[54:57], v[148:151], v[188:191], v[54:57]
	v_mfma_f32_16x16x32_bf16 v[46:49], v[156:159], v[188:191], v[46:49]
	v_mfma_f32_16x16x32_bf16 v[38:41], v[148:151], v[196:199], v[38:41]
	v_mfma_f32_16x16x32_bf16 v[30:33], v[156:159], v[196:199], v[30:33]
	v_mfma_f32_16x16x32_bf16 v[22:25], v[148:151], v[204:207], v[22:25]
	v_mfma_f32_16x16x32_bf16 v[14:17], v[156:159], v[204:207], v[14:17]
	s_setprio 0
	s_setprio 1
	v_mfma_f32_16x16x32_bf16 v[50:53], v[160:163], v[176:179], 0
	v_mfma_f32_16x16x32_bf16 v[42:45], v[168:171], v[176:179], 0
	v_mfma_f32_16x16x32_bf16 v[34:37], v[160:163], v[184:187], 0
	v_mfma_f32_16x16x32_bf16 v[26:29], v[168:171], v[184:187], 0
	v_mfma_f32_16x16x32_bf16 v[18:21], v[160:163], v[192:195], 0
	v_mfma_f32_16x16x32_bf16 v[10:13], v[168:171], v[192:195], 0
	v_mfma_f32_16x16x32_bf16 v[6:9], v[160:163], v[200:203], 0
	v_mfma_f32_16x16x32_bf16 v[2:5], v[168:171], v[200:203], 0
	v_mfma_f32_16x16x32_bf16 v[50:53], v[164:167], v[180:183], v[50:53]
	v_mfma_f32_16x16x32_bf16 v[42:45], v[172:175], v[180:183], v[42:45]
	v_mfma_f32_16x16x32_bf16 v[34:37], v[164:167], v[188:191], v[34:37]
	v_mfma_f32_16x16x32_bf16 v[26:29], v[172:175], v[188:191], v[26:29]
	v_mfma_f32_16x16x32_bf16 v[18:21], v[164:167], v[196:199], v[18:21]
	v_mfma_f32_16x16x32_bf16 v[10:13], v[172:175], v[196:199], v[10:13]
	v_mfma_f32_16x16x32_bf16 v[6:9], v[164:167], v[204:207], v[6:9]
	s_barrier
	v_mfma_f32_16x16x32_bf16 v[2:5], v[172:175], v[204:207], v[2:5]
	s_setprio 0
	s_add_i32 s6, 0, 0x18000
	s_add_i32 s7, 0, 0x1c000
	v_add_u32_e32 v156, s6, v146
	v_add_u32_e32 v172, s7, v146
	ds_read_b128 v[140:143], v156
	ds_read_b128 v[148:151], v156 offset:1024
	ds_read_b128 v[152:155], v156 offset:2048
	ds_read_b128 v[156:159], v156 offset:3072
	ds_read_b128 v[160:163], v172
	ds_read_b128 v[164:167], v172 offset:1024
	ds_read_b128 v[168:171], v172 offset:2048
	ds_read_b128 v[172:175], v172 offset:3072
	s_add_u32 s4, s36, 0x40000
	s_addc_u32 s5, s37, 0
	s_mov_b32 m0, s45
	v_lshl_add_u64 v[228:229], s[4:5], 0, v[134:135]
	ds_read_b128 v[176:179], v147 offset:32768
	ds_read_b128 v[180:183], v147 offset:33792
	ds_read_b128 v[184:187], v147 offset:34816
	ds_read_b128 v[188:191], v147 offset:35840
	ds_read_b128 v[192:195], v147 offset:36864
	ds_read_b128 v[196:199], v147 offset:37888
	ds_read_b128 v[200:203], v147 offset:38912
	ds_read_b128 v[204:207], v147 offset:39936
	global_load_lds_dwordx4 v[228:229], off
	v_lshl_add_u64 v[228:229], s[4:5], 0, v[130:131]
	s_mov_b32 m0, s46
	s_nop 0
	global_load_lds_dwordx4 v[228:229], off
	s_waitcnt vmcnt(8)
	s_waitcnt lgkmcnt(0)
	s_barrier
	s_setprio 1
	s_waitcnt lgkmcnt(0)
	v_mfma_f32_16x16x32_bf16 v[126:129], v[140:143], v[176:179], v[126:129]
	v_mfma_f32_16x16x32_bf16 v[122:125], v[152:155], v[176:179], v[122:125]
	v_mfma_f32_16x16x32_bf16 v[118:121], v[140:143], v[184:187], v[118:121]
	v_mfma_f32_16x16x32_bf16 v[110:113], v[152:155], v[184:187], v[110:113]
	v_mfma_f32_16x16x32_bf16 v[102:105], v[140:143], v[192:195], v[102:105]
	v_mfma_f32_16x16x32_bf16 v[94:97], v[152:155], v[192:195], v[94:97]
	v_mfma_f32_16x16x32_bf16 v[86:89], v[140:143], v[200:203], v[86:89]
	v_mfma_f32_16x16x32_bf16 v[78:81], v[152:155], v[200:203], v[78:81]
	v_mfma_f32_16x16x32_bf16 v[126:129], v[148:151], v[180:183], v[126:129]
	v_mfma_f32_16x16x32_bf16 v[122:125], v[156:159], v[180:183], v[122:125]
	v_mfma_f32_16x16x32_bf16 v[118:121], v[148:151], v[188:191], v[118:121]
	v_mfma_f32_16x16x32_bf16 v[110:113], v[156:159], v[188:191], v[110:113]
	v_mfma_f32_16x16x32_bf16 v[102:105], v[148:151], v[196:199], v[102:105]
	v_mfma_f32_16x16x32_bf16 v[94:97], v[156:159], v[196:199], v[94:97]
	v_mfma_f32_16x16x32_bf16 v[86:89], v[148:151], v[204:207], v[86:89]
	v_mfma_f32_16x16x32_bf16 v[78:81], v[156:159], v[204:207], v[78:81]
	s_setprio 0
	s_setprio 1
	v_mfma_f32_16x16x32_bf16 v[114:117], v[160:163], v[176:179], v[114:117]
	v_mfma_f32_16x16x32_bf16 v[106:109], v[168:171], v[176:179], v[106:109]
	v_mfma_f32_16x16x32_bf16 v[98:101], v[160:163], v[184:187], v[98:101]
	v_mfma_f32_16x16x32_bf16 v[90:93], v[168:171], v[184:187], v[90:93]
	v_mfma_f32_16x16x32_bf16 v[82:85], v[160:163], v[192:195], v[82:85]
	v_mfma_f32_16x16x32_bf16 v[74:77], v[168:171], v[192:195], v[74:77]
	v_mfma_f32_16x16x32_bf16 v[70:73], v[160:163], v[200:203], v[70:73]
	v_mfma_f32_16x16x32_bf16 v[66:69], v[168:171], v[200:203], v[66:69]
	v_mfma_f32_16x16x32_bf16 v[114:117], v[164:167], v[180:183], v[114:117]
	v_mfma_f32_16x16x32_bf16 v[106:109], v[172:175], v[180:183], v[106:109]
	v_mfma_f32_16x16x32_bf16 v[98:101], v[164:167], v[188:191], v[98:101]
	v_mfma_f32_16x16x32_bf16 v[90:93], v[172:175], v[188:191], v[90:93]
	v_mfma_f32_16x16x32_bf16 v[82:85], v[164:167], v[196:199], v[82:85]
	v_mfma_f32_16x16x32_bf16 v[74:77], v[172:175], v[196:199], v[74:77]
	v_mfma_f32_16x16x32_bf16 v[70:73], v[164:167], v[204:207], v[70:73]
	s_barrier
	v_mfma_f32_16x16x32_bf16 v[66:69], v[172:175], v[204:207], v[66:69]
	s_setprio 0
	s_add_i32 s4, s6, s38
	v_lshl_add_u64 v[208:209], v[208:209], 0, s[82:83]
	s_mov_b32 m0, s4
	ds_read_b128 v[176:179], v147 offset:49152
	ds_read_b128 v[180:183], v147 offset:50176
	ds_read_b128 v[184:187], v147 offset:51200
	ds_read_b128 v[188:191], v147 offset:52224
	ds_read_b128 v[192:195], v147 offset:53248
	ds_read_b128 v[196:199], v147 offset:54272
	ds_read_b128 v[200:203], v147 offset:55296
	ds_read_b128 v[204:207], v147 offset:56320
	global_load_lds_dwordx4 v[208:209], off
	s_add_i32 m0, s4, 0x2000
	s_add_u32 s4, s34, 0x40080
	v_lshl_add_u64 v[208:209], v[222:223], 0, s[82:83]
	s_addc_u32 s5, s35, 0
	s_add_i32 s6, s7, s38
	global_load_lds_dwordx4 v[208:209], off
	v_lshl_add_u64 v[208:209], s[4:5], 0, v[0:1]
	s_mov_b32 m0, s6
	s_nop 0
	global_load_lds_dwordx4 v[208:209], off
	v_lshl_add_u64 v[208:209], s[4:5], 0, v[132:133]
	s_add_i32 m0, s6, 0x2000
	s_nop 0
	global_load_lds_dwordx4 v[208:209], off
	v_lshl_add_u64 v[208:209], v[224:225], 0, s[82:83]
	s_mov_b32 m0, s49
	s_nop 0
	global_load_lds_dwordx4 v[208:209], off
	v_lshl_add_u64 v[208:209], v[226:227], 0, s[82:83]
	s_mov_b32 m0, s50
	s_nop 0
	global_load_lds_dwordx4 v[208:209], off
	s_waitcnt vmcnt(8)
	s_waitcnt lgkmcnt(0)
	s_barrier
	s_setprio 1
	s_waitcnt lgkmcnt(0)
	v_mfma_f32_16x16x32_bf16 v[62:65], v[140:143], v[176:179], v[62:65]
	v_mfma_f32_16x16x32_bf16 v[58:61], v[152:155], v[176:179], v[58:61]
	v_mfma_f32_16x16x32_bf16 v[54:57], v[140:143], v[184:187], v[54:57]
	v_mfma_f32_16x16x32_bf16 v[46:49], v[152:155], v[184:187], v[46:49]
	v_mfma_f32_16x16x32_bf16 v[38:41], v[140:143], v[192:195], v[38:41]
	v_mfma_f32_16x16x32_bf16 v[30:33], v[152:155], v[192:195], v[30:33]
	v_mfma_f32_16x16x32_bf16 v[22:25], v[140:143], v[200:203], v[22:25]
	v_mfma_f32_16x16x32_bf16 v[14:17], v[152:155], v[200:203], v[14:17]
	v_mfma_f32_16x16x32_bf16 v[62:65], v[148:151], v[180:183], v[62:65]
	v_mfma_f32_16x16x32_bf16 v[58:61], v[156:159], v[180:183], v[58:61]
	v_mfma_f32_16x16x32_bf16 v[54:57], v[148:151], v[188:191], v[54:57]
	v_mfma_f32_16x16x32_bf16 v[46:49], v[156:159], v[188:191], v[46:49]
	v_mfma_f32_16x16x32_bf16 v[38:41], v[148:151], v[196:199], v[38:41]
	v_mfma_f32_16x16x32_bf16 v[30:33], v[156:159], v[196:199], v[30:33]
	v_mfma_f32_16x16x32_bf16 v[22:25], v[148:151], v[204:207], v[22:25]
	v_mfma_f32_16x16x32_bf16 v[14:17], v[156:159], v[204:207], v[14:17]
	s_setprio 0
	s_setprio 1
	v_mfma_f32_16x16x32_bf16 v[50:53], v[160:163], v[176:179], v[50:53]
	v_mfma_f32_16x16x32_bf16 v[42:45], v[168:171], v[176:179], v[42:45]
	v_mfma_f32_16x16x32_bf16 v[34:37], v[160:163], v[184:187], v[34:37]
	v_mfma_f32_16x16x32_bf16 v[26:29], v[168:171], v[184:187], v[26:29]
	v_mfma_f32_16x16x32_bf16 v[18:21], v[160:163], v[192:195], v[18:21]
	v_mfma_f32_16x16x32_bf16 v[10:13], v[168:171], v[192:195], v[10:13]
	v_mfma_f32_16x16x32_bf16 v[6:9], v[160:163], v[200:203], v[6:9]
	v_mfma_f32_16x16x32_bf16 v[2:5], v[168:171], v[200:203], v[2:5]
	v_mfma_f32_16x16x32_bf16 v[50:53], v[164:167], v[180:183], v[50:53]
	v_mfma_f32_16x16x32_bf16 v[42:45], v[172:175], v[180:183], v[42:45]
	v_mfma_f32_16x16x32_bf16 v[34:37], v[164:167], v[188:191], v[34:37]
	v_mfma_f32_16x16x32_bf16 v[26:29], v[172:175], v[188:191], v[26:29]
	v_mfma_f32_16x16x32_bf16 v[18:21], v[164:167], v[196:199], v[18:21]
	v_mfma_f32_16x16x32_bf16 v[10:13], v[172:175], v[196:199], v[10:13]
	v_mfma_f32_16x16x32_bf16 v[6:9], v[164:167], v[204:207], v[6:9]
	s_barrier
	v_mfma_f32_16x16x32_bf16 v[2:5], v[172:175], v[204:207], v[2:5]
	s_setprio 0
	s_add_i32 s59, s59, 2
	s_add_u32 s30, s30, 0x100
	s_addc_u32 s31, s31, 0
	s_add_u32 s68, s68, 0x100
	s_addc_u32 s69, s69, 0
	s_cmp_gt_u32 s59, 13
